# v36: v34 with the layer-B projection prefetch covering two complete rows (rinv, cos, sin of rows 0 and 1) so the first four stores per wave go out while the remaining row operands are still in flight
# baseline (speedup 1.0000x reference)
.Lb1_ph3:
	s_add_i32 s50, 16, 0x18000
	v_add_u32_e32 v151, s50, v176
	s_add_i32 s51, 16, 0x1c000
	ds_read_b128 v[132:135], v151
	ds_read_b128 v[152:155], v151 offset:1024
	ds_read_b128 v[156:159], v151 offset:2048
	ds_read_b128 v[160:163], v151 offset:3072
	v_add_u32_e32 v151, s51, v176
	ds_read_b128 v[164:167], v151
	ds_read_b128 v[168:171], v151 offset:1024
	ds_read_b128 v[172:175], v151 offset:2048
	ds_read_b128 v[180:183], v151 offset:3072
	s_mov_b32 m0, s37
	s_nop 0
	global_load_lds_dwordx4 v[220:221], off
	s_mov_b32 m0, s38
	s_nop 0
	global_load_lds_dwordx4 v[224:225], off
	s_add_u32 s8, s8, 0x40000
	s_addc_u32 s9, s9, 0
	s_mov_b32 m0, s39
	v_lshl_add_u64 v[226:227], s[8:9], 0, v[140:141]
	ds_read_b128 v[184:187], v178 offset:32768
	ds_read_b128 v[188:191], v178 offset:33792
	ds_read_b128 v[192:195], v178 offset:34816
	ds_read_b128 v[196:199], v178 offset:35840
	ds_read_b128 v[200:203], v178 offset:36864
	ds_read_b128 v[204:207], v178 offset:37888
	ds_read_b128 v[208:211], v178 offset:38912
	ds_read_b128 v[212:215], v178 offset:39936
	global_load_lds_dwordx4 v[226:227], off
	v_lshl_add_u64 v[226:227], s[8:9], 0, v[136:137]
	s_mov_b32 m0, s40
	s_nop 0
	global_load_lds_dwordx4 v[226:227], off
	s_waitcnt vmcnt(8)
	s_cmp_eq_u32 s49, 12
	s_cbranch_scc0 .Lb1pf_skip
	v_lshl_add_u32 v246, s2, 8, v3
	v_lshlrev_b32_e32 v230, 7, v246
	v_lshlrev_b32_e32 v246, 2, v246
	global_load_dword v228, v246, s[16:17]
	global_load_dword v229, v246, s[16:17] offset:64
	v_add_co_u32_e32 v252, vcc, v144, v230
	s_nop 1
	v_addc_co_u32_e32 v253, vcc, 0, v145, vcc
	v_add_co_u32_e32 v244, vcc, 0x200000, v252
	s_nop 1
	v_addc_co_u32_e32 v245, vcc, 0, v253, vcc
	global_load_dwordx4 v[236:239], v[252:253], off
	global_load_dwordx4 v[248:251], v[252:253], off offset:2048
	global_load_dwordx4 v[240:243], v[244:245], off
	global_load_dwordx2 v[252:253], v[244:245], off offset:2056
	global_load_dwordx2 v[244:245], v[244:245], off offset:2048

.Lb1w4_last:
	s_waitcnt vmcnt(15)

.LBB0_163:
	v_lshlrev_b32_e32 v153, 2, v152
	global_load_dword v182, v153, s[16:17] offset:128
	global_load_dword v183, v153, s[16:17] offset:192
	global_load_dword v184, v153, s[16:17] offset:512
	global_load_dword v185, v153, s[16:17] offset:576
	global_load_dword v186, v153, s[16:17] offset:640
	global_load_dword v187, v153, s[16:17] offset:704
	s_mul_hi_i32 s6, s48, 0x2aaaaaab
	s_lshr_b32 s7, s6, 31
	s_ashr_i32 s6, s6, 1
	s_add_i32 s9, s6, s7
	s_mul_i32 s6, s9, 12
	s_sub_i32 s6, s48, s6
	s_ashr_i32 s21, s6, 2
	s_sub_u32 s0, s41, 0x4d00000
	s_subb_u32 s1, s43, 0
	s_add_u32 s2, s0, 0x200000
	s_addc_u32 s3, s1, 0
	s_cmp_gt_i32 s21, 1
	s_cbranch_scc1 .Lb1q_vonly
	v_subrev_u32_e32 v154, s0, v144
	v_lshl_add_u32 v155, v152, 7, v154
	v_add_u32_e32 v156, 0x1000, v155
	global_load_dwordx4 v[204:207], v156, s[0:1]
	global_load_dwordx4 v[208:211], v156, s[2:3]
	global_load_dwordx4 v[212:215], v156, s[0:1] offset:2048
	global_load_dwordx4 v[216:219], v156, s[2:3] offset:2048
	s_lshl_b32 s23, s48, 2
	s_and_b32 s23, s23, 12
	s_or_b32 s23, s23, s46
	s_lshl_b32 s28, s9, 1
	s_sub_i32 s29, 14, s28
	s_cmp_eq_u32 s21, 2
	s_cselect_b32 s7, 1, 0
	s_or_b32 s7, s28, s7
	s_cmp_eq_u32 s21, 0
	s_cselect_b32 s6, s9, s7
	s_cselect_b32 s8, 0, 0x6000000
	s_cselect_b32 s7, 0x3e38aa3b, 1.0
	v_mov_b32_e32 v179, s7
	s_add_u32 s8, s41, s8
	s_addc_u32 s9, s43, 0
	s_mov_b32 s7, 0
	s_lshl_b64 s[6:7], s[6:7], 25
	s_add_u32 s6, s8, s6
	s_addc_u32 s7, s9, s7
	s_lshl_b32 s8, s23, 21
	s_add_u32 s6, s6, s8
	s_addc_u32 s7, s7, 0
	s_add_u32 s8, s6, 0x400000
	s_addc_u32 s9, s7, 0
	v_lshlrev_b32_e32 v151, s29, v152
	v_and_b32_e32 v151, 0x3fff, v151
	v_lshrrev_b32_e32 v159, s28, v152
	v_add_u32_e32 v151, v151, v159
	v_lshl_add_u32 v160, v151, 7, v150
	s_lshr_b32 s21, 0x800, s28
	s_lshr_b32 s23, 0x4000, s28
	v_add_u32_e32 v161, s21, v160
	v_add_u32_e32 v162, s21, v161
	v_add_u32_e32 v163, s21, v162
	v_add_u32_e32 v164, s23, v160
	v_add_u32_e32 v165, s21, v164
	v_add_u32_e32 v166, s21, v165
	v_add_u32_e32 v167, s21, v166
	v_add_u32_e32 v157, 0x4000, v155
	v_add_u32_e32 v158, 0x5000, v155
	s_waitcnt vmcnt(10)
	v_mul_f32_e32 v220, v179, v228
	v_pk_mul_f32 v[236:237], v[220:221], v[236:237] op_sel_hi:[0,1]
	v_pk_mul_f32 v[238:239], v[220:221], v[238:239] op_sel_hi:[0,1]
	v_pk_mul_f32 v[240:241], v[220:221], v[240:241] op_sel_hi:[0,1]
	v_pk_mul_f32 v[242:243], v[220:221], v[242:243] op_sel_hi:[0,1]
	v_pk_mul_f32 v[132:133], v[128:129], v[236:237]
	v_pk_mul_f32 v[134:135], v[130:131], v[238:239]
	v_pk_mul_f32 v[224:225], v[124:125], v[236:237]
	v_pk_mul_f32 v[226:227], v[126:127], v[238:239]
	v_pk_fma_f32 v[132:133], v[124:125], v[240:241], v[132:133] neg_lo:[1,0,0] neg_hi:[1,0,0]
	v_pk_fma_f32 v[134:135], v[126:127], v[242:243], v[134:135] neg_lo:[1,0,0] neg_hi:[1,0,0]
	v_pk_fma_f32 v[224:225], v[128:129], v[240:241], v[224:225]
	v_pk_fma_f32 v[226:227], v[130:131], v[242:243], v[226:227]
	v_cvt_pk_bf16_f32 v128, v132, v133
	v_cvt_pk_bf16_f32 v129, v134, v135
	v_cvt_pk_bf16_f32 v130, v224, v225
	v_cvt_pk_bf16_f32 v131, v226, v227
	global_store_dwordx4 v160, v[128:131], s[6:7]
	v_pk_mul_f32 v[168:169], v[120:121], v[236:237]
	v_pk_mul_f32 v[170:171], v[122:123], v[238:239]
	v_pk_mul_f32 v[172:173], v[116:117], v[236:237]
	v_pk_mul_f32 v[174:175], v[118:119], v[238:239]
	v_pk_fma_f32 v[168:169], v[116:117], v[240:241], v[168:169] neg_lo:[1,0,0] neg_hi:[1,0,0]
	v_pk_fma_f32 v[170:171], v[118:119], v[242:243], v[170:171] neg_lo:[1,0,0] neg_hi:[1,0,0]
	v_pk_fma_f32 v[172:173], v[120:121], v[240:241], v[172:173]
	v_pk_fma_f32 v[174:175], v[122:123], v[242:243], v[174:175]
	v_cvt_pk_bf16_f32 v120, v168, v169
	v_cvt_pk_bf16_f32 v121, v170, v171
	v_cvt_pk_bf16_f32 v122, v172, v173
	v_cvt_pk_bf16_f32 v123, v174, v175
	global_store_dwordx4 v160, v[120:123], s[8:9]
	v_mul_f32_e32 v220, v179, v229
	v_pk_mul_f32 v[248:249], v[220:221], v[248:249] op_sel_hi:[0,1]
	v_pk_mul_f32 v[250:251], v[220:221], v[250:251] op_sel_hi:[0,1]
	v_pk_mul_f32 v[244:245], v[220:221], v[244:245] op_sel_hi:[0,1]
	v_pk_mul_f32 v[252:253], v[220:221], v[252:253] op_sel_hi:[0,1]
	v_pk_mul_f32 v[132:133], v[112:113], v[248:249]
	v_pk_mul_f32 v[134:135], v[114:115], v[250:251]
	v_pk_mul_f32 v[224:225], v[108:109], v[248:249]
	v_pk_mul_f32 v[226:227], v[110:111], v[250:251]
	v_pk_fma_f32 v[132:133], v[108:109], v[244:245], v[132:133] neg_lo:[1,0,0] neg_hi:[1,0,0]
	v_pk_fma_f32 v[134:135], v[110:111], v[252:253], v[134:135] neg_lo:[1,0,0] neg_hi:[1,0,0]
	v_pk_fma_f32 v[224:225], v[112:113], v[244:245], v[224:225]
	v_pk_fma_f32 v[226:227], v[114:115], v[252:253], v[226:227]
	v_cvt_pk_bf16_f32 v112, v132, v133
	v_cvt_pk_bf16_f32 v113, v134, v135
	v_cvt_pk_bf16_f32 v114, v224, v225
	v_cvt_pk_bf16_f32 v115, v226, v227
	global_store_dwordx4 v161, v[112:115], s[6:7]
	v_pk_mul_f32 v[168:169], v[104:105], v[248:249]
	v_pk_mul_f32 v[170:171], v[106:107], v[250:251]
	v_pk_mul_f32 v[172:173], v[100:101], v[248:249]
	v_pk_mul_f32 v[174:175], v[102:103], v[250:251]
	v_pk_fma_f32 v[168:169], v[100:101], v[244:245], v[168:169] neg_lo:[1,0,0] neg_hi:[1,0,0]
	v_pk_fma_f32 v[170:171], v[102:103], v[252:253], v[170:171] neg_lo:[1,0,0] neg_hi:[1,0,0]
	v_pk_fma_f32 v[172:173], v[104:105], v[244:245], v[172:173]
	v_pk_fma_f32 v[174:175], v[106:107], v[252:253], v[174:175]
	v_cvt_pk_bf16_f32 v104, v168, v169
	v_cvt_pk_bf16_f32 v105, v170, v171
	v_cvt_pk_bf16_f32 v106, v172, v173
	v_cvt_pk_bf16_f32 v107, v174, v175
	global_store_dwordx4 v161, v[104:107], s[8:9]
	global_load_dwordx4 v[100:103], v157, s[0:1]
	global_load_dwordx4 v[104:107], v157, s[2:3]
	global_load_dwordx4 v[108:111], v157, s[0:1] offset:2048
	global_load_dwordx4 v[112:115], v157, s[2:3] offset:2048
	global_load_dwordx4 v[116:119], v158, s[0:1]
	global_load_dwordx4 v[120:123], v158, s[2:3]
	global_load_dwordx4 v[124:127], v158, s[0:1] offset:2048
	global_load_dwordx4 v[128:131], v158, s[2:3] offset:2048
	s_waitcnt vmcnt(14)
	v_mul_f32_e32 v220, v179, v182
	v_pk_mul_f32 v[204:205], v[220:221], v[204:205] op_sel_hi:[0,1]
	v_pk_mul_f32 v[206:207], v[220:221], v[206:207] op_sel_hi:[0,1]
	v_pk_mul_f32 v[208:209], v[220:221], v[208:209] op_sel_hi:[0,1]
	v_pk_mul_f32 v[210:211], v[220:221], v[210:211] op_sel_hi:[0,1]
	v_pk_mul_f32 v[132:133], v[96:97], v[204:205]
	v_pk_mul_f32 v[134:135], v[98:99], v[206:207]
	v_pk_mul_f32 v[224:225], v[92:93], v[204:205]
	v_pk_mul_f32 v[226:227], v[94:95], v[206:207]
	v_pk_fma_f32 v[132:133], v[92:93], v[208:209], v[132:133] neg_lo:[1,0,0] neg_hi:[1,0,0]
	v_pk_fma_f32 v[134:135], v[94:95], v[210:211], v[134:135] neg_lo:[1,0,0] neg_hi:[1,0,0]
	v_pk_fma_f32 v[224:225], v[96:97], v[208:209], v[224:225]
	v_pk_fma_f32 v[226:227], v[98:99], v[210:211], v[226:227]
	v_cvt_pk_bf16_f32 v96, v132, v133
	v_cvt_pk_bf16_f32 v97, v134, v135
	v_cvt_pk_bf16_f32 v98, v224, v225
	v_cvt_pk_bf16_f32 v99, v226, v227
	global_store_dwordx4 v162, v[96:99], s[6:7]
	v_pk_mul_f32 v[168:169], v[88:89], v[204:205]
	v_pk_mul_f32 v[170:171], v[90:91], v[206:207]
	v_pk_mul_f32 v[172:173], v[84:85], v[204:205]
	v_pk_mul_f32 v[174:175], v[86:87], v[206:207]
	v_pk_fma_f32 v[168:169], v[84:85], v[208:209], v[168:169] neg_lo:[1,0,0] neg_hi:[1,0,0]
	v_pk_fma_f32 v[170:171], v[86:87], v[210:211], v[170:171] neg_lo:[1,0,0] neg_hi:[1,0,0]
	v_pk_fma_f32 v[172:173], v[88:89], v[208:209], v[172:173]
	v_pk_fma_f32 v[174:175], v[90:91], v[210:211], v[174:175]
	v_cvt_pk_bf16_f32 v88, v168, v169
	v_cvt_pk_bf16_f32 v89, v170, v171
	v_cvt_pk_bf16_f32 v90, v172, v173
	v_cvt_pk_bf16_f32 v91, v174, v175
	global_store_dwordx4 v162, v[88:91], s[8:9]
	s_waitcnt vmcnt(14)
	v_mul_f32_e32 v220, v179, v183
	v_pk_mul_f32 v[212:213], v[220:221], v[212:213] op_sel_hi:[0,1]
	v_pk_mul_f32 v[214:215], v[220:221], v[214:215] op_sel_hi:[0,1]
	v_pk_mul_f32 v[216:217], v[220:221], v[216:217] op_sel_hi:[0,1]
	v_pk_mul_f32 v[218:219], v[220:221], v[218:219] op_sel_hi:[0,1]
	v_pk_mul_f32 v[132:133], v[80:81], v[212:213]
	v_pk_mul_f32 v[134:135], v[82:83], v[214:215]
	v_pk_mul_f32 v[224:225], v[76:77], v[212:213]
	v_pk_mul_f32 v[226:227], v[78:79], v[214:215]
	v_pk_fma_f32 v[132:133], v[76:77], v[216:217], v[132:133] neg_lo:[1,0,0] neg_hi:[1,0,0]
	v_pk_fma_f32 v[134:135], v[78:79], v[218:219], v[134:135] neg_lo:[1,0,0] neg_hi:[1,0,0]
	v_pk_fma_f32 v[224:225], v[80:81], v[216:217], v[224:225]
	v_pk_fma_f32 v[226:227], v[82:83], v[218:219], v[226:227]
	v_cvt_pk_bf16_f32 v80, v132, v133
	v_cvt_pk_bf16_f32 v81, v134, v135
	v_cvt_pk_bf16_f32 v82, v224, v225
	v_cvt_pk_bf16_f32 v83, v226, v227
	global_store_dwordx4 v163, v[80:83], s[6:7]
	v_pk_mul_f32 v[168:169], v[72:73], v[212:213]
	v_pk_mul_f32 v[170:171], v[74:75], v[214:215]
	v_pk_mul_f32 v[172:173], v[68:69], v[212:213]
	v_pk_mul_f32 v[174:175], v[70:71], v[214:215]
	v_pk_fma_f32 v[168:169], v[68:69], v[216:217], v[168:169] neg_lo:[1,0,0] neg_hi:[1,0,0]
	v_pk_fma_f32 v[170:171], v[70:71], v[218:219], v[170:171] neg_lo:[1,0,0] neg_hi:[1,0,0]
	v_pk_fma_f32 v[172:173], v[72:73], v[216:217], v[172:173]
	v_pk_fma_f32 v[174:175], v[74:75], v[218:219], v[174:175]
	v_cvt_pk_bf16_f32 v72, v168, v169
	v_cvt_pk_bf16_f32 v73, v170, v171
	v_cvt_pk_bf16_f32 v74, v172, v173
	v_cvt_pk_bf16_f32 v75, v174, v175
	global_store_dwordx4 v163, v[72:75], s[8:9]
	s_waitcnt vmcnt(10)
	v_mul_f32_e32 v220, v179, v184
	v_pk_mul_f32 v[100:101], v[220:221], v[100:101] op_sel_hi:[0,1]
	v_pk_mul_f32 v[102:103], v[220:221], v[102:103] op_sel_hi:[0,1]
	v_pk_mul_f32 v[104:105], v[220:221], v[104:105] op_sel_hi:[0,1]
	v_pk_mul_f32 v[106:107], v[220:221], v[106:107] op_sel_hi:[0,1]
	v_pk_mul_f32 v[132:133], v[64:65], v[100:101]
	v_pk_mul_f32 v[134:135], v[66:67], v[102:103]
	v_pk_mul_f32 v[224:225], v[60:61], v[100:101]
	v_pk_mul_f32 v[226:227], v[62:63], v[102:103]
	v_pk_fma_f32 v[132:133], v[60:61], v[104:105], v[132:133] neg_lo:[1,0,0] neg_hi:[1,0,0]
	v_pk_fma_f32 v[134:135], v[62:63], v[106:107], v[134:135] neg_lo:[1,0,0] neg_hi:[1,0,0]
	v_pk_fma_f32 v[224:225], v[64:65], v[104:105], v[224:225]
	v_pk_fma_f32 v[226:227], v[66:67], v[106:107], v[226:227]
	v_cvt_pk_bf16_f32 v64, v132, v133
	v_cvt_pk_bf16_f32 v65, v134, v135
	v_cvt_pk_bf16_f32 v66, v224, v225
	v_cvt_pk_bf16_f32 v67, v226, v227
	global_store_dwordx4 v164, v[64:67], s[6:7]
	v_pk_mul_f32 v[168:169], v[56:57], v[100:101]
	v_pk_mul_f32 v[170:171], v[58:59], v[102:103]
	v_pk_mul_f32 v[172:173], v[52:53], v[100:101]
	v_pk_mul_f32 v[174:175], v[54:55], v[102:103]
	v_pk_fma_f32 v[168:169], v[52:53], v[104:105], v[168:169] neg_lo:[1,0,0] neg_hi:[1,0,0]
	v_pk_fma_f32 v[170:171], v[54:55], v[106:107], v[170:171] neg_lo:[1,0,0] neg_hi:[1,0,0]
	v_pk_fma_f32 v[172:173], v[56:57], v[104:105], v[172:173]
	v_pk_fma_f32 v[174:175], v[58:59], v[106:107], v[174:175]
	v_cvt_pk_bf16_f32 v56, v168, v169
	v_cvt_pk_bf16_f32 v57, v170, v171
	v_cvt_pk_bf16_f32 v58, v172, v173
	v_cvt_pk_bf16_f32 v59, v174, v175
	global_store_dwordx4 v164, v[56:59], s[8:9]
	s_waitcnt vmcnt(10)
	v_mul_f32_e32 v220, v179, v185
	v_pk_mul_f32 v[108:109], v[220:221], v[108:109] op_sel_hi:[0,1]
	v_pk_mul_f32 v[110:111], v[220:221], v[110:111] op_sel_hi:[0,1]
	v_pk_mul_f32 v[112:113], v[220:221], v[112:113] op_sel_hi:[0,1]
	v_pk_mul_f32 v[114:115], v[220:221], v[114:115] op_sel_hi:[0,1]
	v_pk_mul_f32 v[132:133], v[48:49], v[108:109]
	v_pk_mul_f32 v[134:135], v[50:51], v[110:111]
	v_pk_mul_f32 v[224:225], v[44:45], v[108:109]
	v_pk_mul_f32 v[226:227], v[46:47], v[110:111]
	v_pk_fma_f32 v[132:133], v[44:45], v[112:113], v[132:133] neg_lo:[1,0,0] neg_hi:[1,0,0]
	v_pk_fma_f32 v[134:135], v[46:47], v[114:115], v[134:135] neg_lo:[1,0,0] neg_hi:[1,0,0]
	v_pk_fma_f32 v[224:225], v[48:49], v[112:113], v[224:225]
	v_pk_fma_f32 v[226:227], v[50:51], v[114:115], v[226:227]
	v_cvt_pk_bf16_f32 v48, v132, v133
	v_cvt_pk_bf16_f32 v49, v134, v135
	v_cvt_pk_bf16_f32 v50, v224, v225
	v_cvt_pk_bf16_f32 v51, v226, v227
	global_store_dwordx4 v165, v[48:51], s[6:7]
	v_pk_mul_f32 v[168:169], v[40:41], v[108:109]
	v_pk_mul_f32 v[170:171], v[42:43], v[110:111]
	v_pk_mul_f32 v[172:173], v[36:37], v[108:109]
	v_pk_mul_f32 v[174:175], v[38:39], v[110:111]
	v_pk_fma_f32 v[168:169], v[36:37], v[112:113], v[168:169] neg_lo:[1,0,0] neg_hi:[1,0,0]
	v_pk_fma_f32 v[170:171], v[38:39], v[114:115], v[170:171] neg_lo:[1,0,0] neg_hi:[1,0,0]
	v_pk_fma_f32 v[172:173], v[40:41], v[112:113], v[172:173]
	v_pk_fma_f32 v[174:175], v[42:43], v[114:115], v[174:175]
	v_cvt_pk_bf16_f32 v40, v168, v169
	v_cvt_pk_bf16_f32 v41, v170, v171
	v_cvt_pk_bf16_f32 v42, v172, v173
	v_cvt_pk_bf16_f32 v43, v174, v175
	global_store_dwordx4 v165, v[40:43], s[8:9]
	s_waitcnt vmcnt(10)
	v_mul_f32_e32 v220, v179, v186
	v_pk_mul_f32 v[116:117], v[220:221], v[116:117] op_sel_hi:[0,1]
	v_pk_mul_f32 v[118:119], v[220:221], v[118:119] op_sel_hi:[0,1]
	v_pk_mul_f32 v[120:121], v[220:221], v[120:121] op_sel_hi:[0,1]
	v_pk_mul_f32 v[122:123], v[220:221], v[122:123] op_sel_hi:[0,1]
	v_pk_mul_f32 v[132:133], v[32:33], v[116:117]
	v_pk_mul_f32 v[134:135], v[34:35], v[118:119]
	v_pk_mul_f32 v[224:225], v[28:29], v[116:117]
	v_pk_mul_f32 v[226:227], v[30:31], v[118:119]
	v_pk_fma_f32 v[132:133], v[28:29], v[120:121], v[132:133] neg_lo:[1,0,0] neg_hi:[1,0,0]
	v_pk_fma_f32 v[134:135], v[30:31], v[122:123], v[134:135] neg_lo:[1,0,0] neg_hi:[1,0,0]
	v_pk_fma_f32 v[224:225], v[32:33], v[120:121], v[224:225]
	v_pk_fma_f32 v[226:227], v[34:35], v[122:123], v[226:227]
	v_cvt_pk_bf16_f32 v32, v132, v133
	v_cvt_pk_bf16_f32 v33, v134, v135
	v_cvt_pk_bf16_f32 v34, v224, v225
	v_cvt_pk_bf16_f32 v35, v226, v227
	global_store_dwordx4 v166, v[32:35], s[6:7]
	v_pk_mul_f32 v[168:169], v[24:25], v[116:117]
	v_pk_mul_f32 v[170:171], v[26:27], v[118:119]
	v_pk_mul_f32 v[172:173], v[20:21], v[116:117]
	v_pk_mul_f32 v[174:175], v[22:23], v[118:119]
	v_pk_fma_f32 v[168:169], v[20:21], v[120:121], v[168:169] neg_lo:[1,0,0] neg_hi:[1,0,0]
	v_pk_fma_f32 v[170:171], v[22:23], v[122:123], v[170:171] neg_lo:[1,0,0] neg_hi:[1,0,0]
	v_pk_fma_f32 v[172:173], v[24:25], v[120:121], v[172:173]
	v_pk_fma_f32 v[174:175], v[26:27], v[122:123], v[174:175]
	v_cvt_pk_bf16_f32 v24, v168, v169
	v_cvt_pk_bf16_f32 v25, v170, v171
	v_cvt_pk_bf16_f32 v26, v172, v173
	v_cvt_pk_bf16_f32 v27, v174, v175
	global_store_dwordx4 v166, v[24:27], s[8:9]
	s_waitcnt vmcnt(10)
	v_mul_f32_e32 v220, v179, v187
	v_pk_mul_f32 v[124:125], v[220:221], v[124:125] op_sel_hi:[0,1]
	v_pk_mul_f32 v[126:127], v[220:221], v[126:127] op_sel_hi:[0,1]
	v_pk_mul_f32 v[128:129], v[220:221], v[128:129] op_sel_hi:[0,1]
	v_pk_mul_f32 v[130:131], v[220:221], v[130:131] op_sel_hi:[0,1]
	v_pk_mul_f32 v[132:133], v[16:17], v[124:125]
	v_pk_mul_f32 v[134:135], v[18:19], v[126:127]
	v_pk_mul_f32 v[224:225], v[12:13], v[124:125]
	v_pk_mul_f32 v[226:227], v[14:15], v[126:127]
	v_pk_fma_f32 v[132:133], v[12:13], v[128:129], v[132:133] neg_lo:[1,0,0] neg_hi:[1,0,0]
	v_pk_fma_f32 v[134:135], v[14:15], v[130:131], v[134:135] neg_lo:[1,0,0] neg_hi:[1,0,0]
	v_pk_fma_f32 v[224:225], v[16:17], v[128:129], v[224:225]
	v_pk_fma_f32 v[226:227], v[18:19], v[130:131], v[226:227]
	v_cvt_pk_bf16_f32 v16, v132, v133
	v_cvt_pk_bf16_f32 v17, v134, v135
	v_cvt_pk_bf16_f32 v18, v224, v225
	v_cvt_pk_bf16_f32 v19, v226, v227
	global_store_dwordx4 v167, v[16:19], s[6:7]
	v_pk_mul_f32 v[168:169], v[8:9], v[124:125]
	v_pk_mul_f32 v[170:171], v[10:11], v[126:127]
	v_pk_mul_f32 v[172:173], v[4:5], v[124:125]
	v_pk_mul_f32 v[174:175], v[6:7], v[126:127]
	v_pk_fma_f32 v[168:169], v[4:5], v[128:129], v[168:169] neg_lo:[1,0,0] neg_hi:[1,0,0]
	v_pk_fma_f32 v[170:171], v[6:7], v[130:131], v[170:171] neg_lo:[1,0,0] neg_hi:[1,0,0]
	v_pk_fma_f32 v[172:173], v[8:9], v[128:129], v[172:173]
	v_pk_fma_f32 v[174:175], v[10:11], v[130:131], v[174:175]
	v_cvt_pk_bf16_f32 v8, v168, v169
	v_cvt_pk_bf16_f32 v9, v170, v171
	v_cvt_pk_bf16_f32 v10, v172, v173
	v_cvt_pk_bf16_f32 v11, v174, v175
	global_store_dwordx4 v167, v[8:11], s[8:9]
	s_branch .Lb1q_done
.Lb1q_vonly:
	s_lshl_b32 s23, s48, 2
	s_and_b32 s23, s23, 12
	s_or_b32 s23, s23, s46
	s_lshl_b32 s28, s9, 1
	s_sub_i32 s29, 14, s28
	s_cmp_eq_u32 s21, 2
	s_cselect_b32 s7, 1, 0
	s_or_b32 s7, s28, s7
	s_cmp_eq_u32 s21, 0
	s_cselect_b32 s6, s9, s7
	s_cselect_b32 s8, 0, 0x6000000
	s_cselect_b32 s7, 0x3e38aa3b, 1.0
	v_mov_b32_e32 v179, s7
	s_add_u32 s8, s41, s8
	s_addc_u32 s9, s43, 0
	s_mov_b32 s7, 0
	s_lshl_b64 s[6:7], s[6:7], 25
	s_add_u32 s6, s8, s6
	s_addc_u32 s7, s9, s7
	s_lshl_b32 s8, s23, 21
	s_add_u32 s6, s6, s8
	s_addc_u32 s7, s7, 0
	s_add_u32 s8, s6, 0x400000
	s_addc_u32 s9, s7, 0
	v_lshlrev_b32_e32 v151, s29, v152
	v_and_b32_e32 v151, 0x3fff, v151
	v_lshrrev_b32_e32 v159, s28, v152
	v_add_u32_e32 v151, v151, v159
	v_lshl_add_u32 v160, v151, 7, v150
	s_lshr_b32 s21, 0x800, s28
	s_lshr_b32 s23, 0x4000, s28
	v_add_u32_e32 v161, s21, v160
	v_add_u32_e32 v162, s21, v161
	v_add_u32_e32 v163, s21, v162
	v_add_u32_e32 v164, s23, v160
	v_add_u32_e32 v165, s21, v164
	v_add_u32_e32 v166, s21, v165
	v_add_u32_e32 v167, s21, v166
	s_waitcnt vmcnt(6)
	v_mul_f32_e32 v220, v179, v228
	v_pk_mul_f32 v[128:129], v[128:129], v[220:221] op_sel_hi:[1,0]
	v_pk_mul_f32 v[130:131], v[130:131], v[220:221] op_sel_hi:[1,0]
	v_pk_mul_f32 v[124:125], v[124:125], v[220:221] op_sel_hi:[1,0]
	v_pk_mul_f32 v[126:127], v[126:127], v[220:221] op_sel_hi:[1,0]
	v_cvt_pk_bf16_f32 v128, v128, v129
	v_cvt_pk_bf16_f32 v129, v130, v131
	v_cvt_pk_bf16_f32 v130, v124, v125
	v_cvt_pk_bf16_f32 v131, v126, v127
	global_store_dwordx4 v160, v[128:131], s[6:7]
	v_pk_mul_f32 v[120:121], v[120:121], v[220:221] op_sel_hi:[1,0]
	v_pk_mul_f32 v[122:123], v[122:123], v[220:221] op_sel_hi:[1,0]
	v_pk_mul_f32 v[116:117], v[116:117], v[220:221] op_sel_hi:[1,0]
	v_pk_mul_f32 v[118:119], v[118:119], v[220:221] op_sel_hi:[1,0]
	v_cvt_pk_bf16_f32 v120, v120, v121
	v_cvt_pk_bf16_f32 v121, v122, v123
	v_cvt_pk_bf16_f32 v122, v116, v117
	v_cvt_pk_bf16_f32 v123, v118, v119
	global_store_dwordx4 v160, v[120:123], s[8:9]
	v_mul_f32_e32 v220, v179, v229
	v_pk_mul_f32 v[112:113], v[112:113], v[220:221] op_sel_hi:[1,0]
	v_pk_mul_f32 v[114:115], v[114:115], v[220:221] op_sel_hi:[1,0]
	v_pk_mul_f32 v[108:109], v[108:109], v[220:221] op_sel_hi:[1,0]
	v_pk_mul_f32 v[110:111], v[110:111], v[220:221] op_sel_hi:[1,0]
	v_cvt_pk_bf16_f32 v112, v112, v113
	v_cvt_pk_bf16_f32 v113, v114, v115
	v_cvt_pk_bf16_f32 v114, v108, v109
	v_cvt_pk_bf16_f32 v115, v110, v111
	global_store_dwordx4 v161, v[112:115], s[6:7]
	v_pk_mul_f32 v[104:105], v[104:105], v[220:221] op_sel_hi:[1,0]
	v_pk_mul_f32 v[106:107], v[106:107], v[220:221] op_sel_hi:[1,0]
	v_pk_mul_f32 v[100:101], v[100:101], v[220:221] op_sel_hi:[1,0]
	v_pk_mul_f32 v[102:103], v[102:103], v[220:221] op_sel_hi:[1,0]
	v_cvt_pk_bf16_f32 v104, v104, v105
	v_cvt_pk_bf16_f32 v105, v106, v107
	v_cvt_pk_bf16_f32 v106, v100, v101
	v_cvt_pk_bf16_f32 v107, v102, v103
	global_store_dwordx4 v161, v[104:107], s[8:9]
	s_waitcnt vmcnt(9)
	v_mul_f32_e32 v220, v179, v182
	v_pk_mul_f32 v[96:97], v[96:97], v[220:221] op_sel_hi:[1,0]
	v_pk_mul_f32 v[98:99], v[98:99], v[220:221] op_sel_hi:[1,0]
	v_pk_mul_f32 v[92:93], v[92:93], v[220:221] op_sel_hi:[1,0]
	v_pk_mul_f32 v[94:95], v[94:95], v[220:221] op_sel_hi:[1,0]
	v_cvt_pk_bf16_f32 v96, v96, v97
	v_cvt_pk_bf16_f32 v97, v98, v99
	v_cvt_pk_bf16_f32 v98, v92, v93
	v_cvt_pk_bf16_f32 v99, v94, v95
	global_store_dwordx4 v162, v[96:99], s[6:7]
	v_pk_mul_f32 v[88:89], v[88:89], v[220:221] op_sel_hi:[1,0]
	v_pk_mul_f32 v[90:91], v[90:91], v[220:221] op_sel_hi:[1,0]
	v_pk_mul_f32 v[84:85], v[84:85], v[220:221] op_sel_hi:[1,0]
	v_pk_mul_f32 v[86:87], v[86:87], v[220:221] op_sel_hi:[1,0]
	v_cvt_pk_bf16_f32 v88, v88, v89
	v_cvt_pk_bf16_f32 v89, v90, v91
	v_cvt_pk_bf16_f32 v90, v84, v85
	v_cvt_pk_bf16_f32 v91, v86, v87
	global_store_dwordx4 v162, v[88:91], s[8:9]
	s_waitcnt vmcnt(10)
	v_mul_f32_e32 v220, v179, v183
	v_pk_mul_f32 v[80:81], v[80:81], v[220:221] op_sel_hi:[1,0]
	v_pk_mul_f32 v[82:83], v[82:83], v[220:221] op_sel_hi:[1,0]
	v_pk_mul_f32 v[76:77], v[76:77], v[220:221] op_sel_hi:[1,0]
	v_pk_mul_f32 v[78:79], v[78:79], v[220:221] op_sel_hi:[1,0]
	v_cvt_pk_bf16_f32 v80, v80, v81
	v_cvt_pk_bf16_f32 v81, v82, v83
	v_cvt_pk_bf16_f32 v82, v76, v77
	v_cvt_pk_bf16_f32 v83, v78, v79
	global_store_dwordx4 v163, v[80:83], s[6:7]
	v_pk_mul_f32 v[72:73], v[72:73], v[220:221] op_sel_hi:[1,0]
	v_pk_mul_f32 v[74:75], v[74:75], v[220:221] op_sel_hi:[1,0]
	v_pk_mul_f32 v[68:69], v[68:69], v[220:221] op_sel_hi:[1,0]
	v_pk_mul_f32 v[70:71], v[70:71], v[220:221] op_sel_hi:[1,0]
	v_cvt_pk_bf16_f32 v72, v72, v73
	v_cvt_pk_bf16_f32 v73, v74, v75
	v_cvt_pk_bf16_f32 v74, v68, v69
	v_cvt_pk_bf16_f32 v75, v70, v71
	global_store_dwordx4 v163, v[72:75], s[8:9]
	s_waitcnt vmcnt(11)
	v_mul_f32_e32 v220, v179, v184
	v_pk_mul_f32 v[64:65], v[64:65], v[220:221] op_sel_hi:[1,0]
	v_pk_mul_f32 v[66:67], v[66:67], v[220:221] op_sel_hi:[1,0]
	v_pk_mul_f32 v[60:61], v[60:61], v[220:221] op_sel_hi:[1,0]
	v_pk_mul_f32 v[62:63], v[62:63], v[220:221] op_sel_hi:[1,0]
	v_cvt_pk_bf16_f32 v64, v64, v65
	v_cvt_pk_bf16_f32 v65, v66, v67
	v_cvt_pk_bf16_f32 v66, v60, v61
	v_cvt_pk_bf16_f32 v67, v62, v63
	global_store_dwordx4 v164, v[64:67], s[6:7]
	v_pk_mul_f32 v[56:57], v[56:57], v[220:221] op_sel_hi:[1,0]
	v_pk_mul_f32 v[58:59], v[58:59], v[220:221] op_sel_hi:[1,0]
	v_pk_mul_f32 v[52:53], v[52:53], v[220:221] op_sel_hi:[1,0]
	v_pk_mul_f32 v[54:55], v[54:55], v[220:221] op_sel_hi:[1,0]
	v_cvt_pk_bf16_f32 v56, v56, v57
	v_cvt_pk_bf16_f32 v57, v58, v59
	v_cvt_pk_bf16_f32 v58, v52, v53
	v_cvt_pk_bf16_f32 v59, v54, v55
	global_store_dwordx4 v164, v[56:59], s[8:9]
	s_waitcnt vmcnt(12)
	v_mul_f32_e32 v220, v179, v185
	v_pk_mul_f32 v[48:49], v[48:49], v[220:221] op_sel_hi:[1,0]
	v_pk_mul_f32 v[50:51], v[50:51], v[220:221] op_sel_hi:[1,0]
	v_pk_mul_f32 v[44:45], v[44:45], v[220:221] op_sel_hi:[1,0]
	v_pk_mul_f32 v[46:47], v[46:47], v[220:221] op_sel_hi:[1,0]
	v_cvt_pk_bf16_f32 v48, v48, v49
	v_cvt_pk_bf16_f32 v49, v50, v51
	v_cvt_pk_bf16_f32 v50, v44, v45
	v_cvt_pk_bf16_f32 v51, v46, v47
	global_store_dwordx4 v165, v[48:51], s[6:7]
	v_pk_mul_f32 v[40:41], v[40:41], v[220:221] op_sel_hi:[1,0]
	v_pk_mul_f32 v[42:43], v[42:43], v[220:221] op_sel_hi:[1,0]
	v_pk_mul_f32 v[36:37], v[36:37], v[220:221] op_sel_hi:[1,0]
	v_pk_mul_f32 v[38:39], v[38:39], v[220:221] op_sel_hi:[1,0]
	v_cvt_pk_bf16_f32 v40, v40, v41
	v_cvt_pk_bf16_f32 v41, v42, v43
	v_cvt_pk_bf16_f32 v42, v36, v37
	v_cvt_pk_bf16_f32 v43, v38, v39
	global_store_dwordx4 v165, v[40:43], s[8:9]
	s_waitcnt vmcnt(13)
	v_mul_f32_e32 v220, v179, v186
	v_pk_mul_f32 v[32:33], v[32:33], v[220:221] op_sel_hi:[1,0]
	v_pk_mul_f32 v[34:35], v[34:35], v[220:221] op_sel_hi:[1,0]
	v_pk_mul_f32 v[28:29], v[28:29], v[220:221] op_sel_hi:[1,0]
	v_pk_mul_f32 v[30:31], v[30:31], v[220:221] op_sel_hi:[1,0]
	v_cvt_pk_bf16_f32 v32, v32, v33
	v_cvt_pk_bf16_f32 v33, v34, v35
	v_cvt_pk_bf16_f32 v34, v28, v29
	v_cvt_pk_bf16_f32 v35, v30, v31
	global_store_dwordx4 v166, v[32:35], s[6:7]
	v_pk_mul_f32 v[24:25], v[24:25], v[220:221] op_sel_hi:[1,0]
	v_pk_mul_f32 v[26:27], v[26:27], v[220:221] op_sel_hi:[1,0]
	v_pk_mul_f32 v[20:21], v[20:21], v[220:221] op_sel_hi:[1,0]
	v_pk_mul_f32 v[22:23], v[22:23], v[220:221] op_sel_hi:[1,0]
	v_cvt_pk_bf16_f32 v24, v24, v25
	v_cvt_pk_bf16_f32 v25, v26, v27
	v_cvt_pk_bf16_f32 v26, v20, v21
	v_cvt_pk_bf16_f32 v27, v22, v23
	global_store_dwordx4 v166, v[24:27], s[8:9]
	s_waitcnt vmcnt(14)
	v_mul_f32_e32 v220, v179, v187
	v_pk_mul_f32 v[16:17], v[16:17], v[220:221] op_sel_hi:[1,0]
	v_pk_mul_f32 v[18:19], v[18:19], v[220:221] op_sel_hi:[1,0]
	v_pk_mul_f32 v[12:13], v[12:13], v[220:221] op_sel_hi:[1,0]
	v_pk_mul_f32 v[14:15], v[14:15], v[220:221] op_sel_hi:[1,0]
	v_cvt_pk_bf16_f32 v16, v16, v17
	v_cvt_pk_bf16_f32 v17, v18, v19
	v_cvt_pk_bf16_f32 v18, v12, v13
	v_cvt_pk_bf16_f32 v19, v14, v15
	global_store_dwordx4 v167, v[16:19], s[6:7]
	v_pk_mul_f32 v[8:9], v[8:9], v[220:221] op_sel_hi:[1,0]
	v_pk_mul_f32 v[10:11], v[10:11], v[220:221] op_sel_hi:[1,0]
	v_pk_mul_f32 v[4:5], v[4:5], v[220:221] op_sel_hi:[1,0]
	v_pk_mul_f32 v[6:7], v[6:7], v[220:221] op_sel_hi:[1,0]
	v_cvt_pk_bf16_f32 v8, v8, v9
	v_cvt_pk_bf16_f32 v9, v10, v11
	v_cvt_pk_bf16_f32 v10, v4, v5
	v_cvt_pk_bf16_f32 v11, v6, v7
	global_store_dwordx4 v167, v[8:11], s[8:9]
